# S21 with 19 pairs of scalar softmax-scale FMAs per iteration packed into v_pk_fma_f32 (as the baseline already does for 8 pairs)
# baseline (speedup 1.0000x reference)
; __device__ __forceinline__ void partialSM(f32x16& p0, f32x16& p1, float& m_reg, float& mn, float& alpha) {
;   constexpr float C = SCALE * 1.4426950408889634f;
;   float pmax = p0[0]; for (int r = 1; r < 16; ++r) pmax = fmaxf(pmax, p0[r]); for (int r = 0; r < 16; ++r) pmax = fmaxf(pmax, p1[r]);
;   { auto rr = __builtin_amdgcn_permlane32_swap(__float_as_uint(pmax), __float_as_uint(pmax), false, false);
;     pmax = fmaxf(__uint_as_float(rr[0]), __uint_as_float(rr[1])); }
;   if (__builtin_expect(__all(pmax - m_reg <= THR / SCALE), 1)) { mn = m_reg; alpha = 1.f; }
;   else { mn = fmaxf(m_reg, pmax); alpha = __builtin_amdgcn_exp2f((m_reg - mn) * C); m_reg = mn; }
;   float mnC = -mn * C;
;   for (int r = 0; r < 16; ++r) p0[r] = fmaf(p0[r], C, mnC); for (int r = 0; r < 16; ++r) p1[r] = fmaf(p1[r], C, mnC);
;   for (int r = 0; r < 16; ++r) p0[r] = __builtin_amdgcn_exp2f(p0[r]);
; }
; __device__ __forceinline__ void finishSM(f32x16& p0, f32x16& p1, float alpha, float& l_reg, bf16x8& pa0, bf16x8& pa1, bf16x8& pa2, bf16x8& pa3) {
;   for (int r = 0; r < 16; ++r) p1[r] = __builtin_amdgcn_exp2f(p1[r]);
;   float ps = 0; for (int r = 0; r < 16; ++r) ps += p0[r]; for (int r = 0; r < 16; ++r) ps += p1[r];
;   { auto rr = __builtin_amdgcn_permlane32_swap(__float_as_uint(ps), __float_as_uint(ps), false, false);
;     ps = __uint_as_float(rr[0]) + __uint_as_float(rr[1]); }
;   l_reg = l_reg * alpha + ps;
;     ...
;   PK4(p0, 0, pa0); PK4(p0, 8, pa1); PK4(p1, 0, pa2); PK4(p1, 8, pa3);
;     ...
; }
; __device__ __forceinline__ void kload(bf16x8 (&kf)[8], const char* Ks, int r32, int hi, int sb) {
; #pragma unroll
;   for (int d0 = 0; d0 < 4; ++d0) { const int cb = sb + (d0 * 16 + hi * 8) * 2;
;     kf[2 * d0] = *reinterpret_cast<const bf16x8*>(Ks + KSWZ(r32, cb)); kf[2 * d0 + 1] = *reinterpret_cast<const bf16x8*>(Ks + KSWZ(32 + r32, cb)); }
; }
; __device__ __forceinline__ void kmma(f32x16& p0, f32x16& p1, const bf16x8 (&kf)[8], const bf16x8* qr) {
;   asm volatile("s_waitcnt lgkmcnt(0)" ::: "memory"); SBAR();
;   p0 = f32x16{}; p1 = f32x16{};
; #pragma unroll
;   for (int d0 = 0; d0 < 4; ++d0) { p0 = __builtin_amdgcn_mfma_f32_32x32x16_bf16(kf[2 * d0], qr[d0], p0, 0, 0, 0); p1 = __builtin_amdgcn_mfma_f32_32x32x16_bf16(kf[2 * d0 + 1], qr[d0], p1, 0, 0, 0); }
; }
; __device__ __forceinline__ void qkt(f32x16& p0, f32x16& p1, const char* Ks, const bf16x8* qr, int r32, int hi, int sb) {
.LBB0_770:
	ds_read_b128 v[82:85], v245
	ds_read_b128 v[86:89], v245 offset:8192
	ds_read_b128 v[130:133], v246
	ds_read_b128 v[134:137], v246 offset:8192
	ds_read_b128 v[206:209], v247
	ds_read_b128 v[210:213], v247 offset:8192
	ds_read_b128 v[214:217], v255
	ds_read_b128 v[218:221], v255 offset:8192
	v_exp_f32_e32 v148, v66
	v_add_f32_e32 v66, 0, v175
	v_add_f32_e32 v66, v177, v66
	v_add_f32_e32 v66, v192, v66
	v_add_f32_e32 v66, v195, v66
	v_add_f32_e32 v66, v196, v66
	v_add_f32_e32 v66, v199, v66
	v_add_f32_e32 v66, v200, v66
	v_add_f32_e32 v66, v203, v66
	v_add_f32_e32 v66, v176, v66
	v_add_f32_e32 v66, v193, v66
	v_add_f32_e32 v66, v194, v66
	v_add_f32_e32 v66, v197, v66
	v_add_f32_e32 v66, v198, v66
	v_exp_f32_e32 v149, v67
	v_add_f32_e32 v66, v201, v66
	s_waitcnt lgkmcnt(7)
	v_mfma_f32_32x32x16_bf16 v[98:113], v[82:85], v[126:129], 0
	v_exp_f32_e32 v150, v68
	s_and_b32 s13, s36, 0xc000
	v_add_f32_e32 v66, v202, v66
	v_add_u32_e32 v244, s13, v164
	v_exp_f32_e32 v151, v69
	ds_read_b64_tr_b16 v[228:229], v244 offset:0
	v_add_f32_e32 v66, v204, v66
	ds_read_b64_tr_b16 v[230:231], v244 offset:0x800
	ds_read_b64_tr_b16 v[232:233], v244 offset:0x1000
	ds_read_b64_tr_b16 v[234:235], v244 offset:0x1800
	s_waitcnt lgkmcnt(10)
	v_mfma_f32_32x32x16_bf16 v[82:97], v[86:89], v[126:129], 0
	v_exp_f32_e32 v186, v70
	ds_read_b64_tr_b16 v[236:237], v244 offset:0x2000
	v_add_f32_e32 v66, v148, v66
	ds_read_b64_tr_b16 v[238:239], v244 offset:0x2800
	v_exp_f32_e32 v187, v71
	ds_read_b64_tr_b16 v[240:241], v244 offset:0x3000
	v_add_f32_e32 v66, v149, v66
	ds_read_b64_tr_b16 v[242:243], v244 offset:0x3800
	v_exp_f32_e32 v188, v72
	s_add_i32 s37, s12, 2
	s_cmpk_lt_u32 s12, 0x7e
	s_cselect_b64 s[0:1], -1, 0
	s_waitcnt lgkmcnt(13)
	v_mfma_f32_32x32x16_bf16 v[98:113], v[130:133], v[122:125], v[98:113]
	v_add_f32_e32 v66, v150, v66
	s_and_b64 s[10:11], s[0:1], exec
	v_exp_f32_e32 v189, v73
	s_cselect_b32 s10, 0, 0xffffff80
	v_add_f32_e32 v66, v151, v66
	s_add_i32 s58, s37, s10
	v_exp_f32_e32 v205, v74
	s_and_b64 s[0:1], s[0:1], exec
	s_cselect_b32 s1, s9, s30
	s_cselect_b32 s0, s8, s26
	s_lshl_b64 s[10:11], s[58:59], 17
	s_waitcnt lgkmcnt(12)
	v_mfma_f32_32x32x16_bf16 v[82:97], v[134:137], v[122:125], v[82:97]
	v_add_f32_e32 v66, v186, v66
	s_lshl_b64 s[0:1], s[0:1], 11
	v_exp_f32_e32 v222, v75
	s_add_u32 s10, s10, s0
	v_add_f32_e32 v66, v187, v66
	s_addc_u32 s11, s11, s1
	v_exp_f32_e32 v223, v76
	s_add_u32 s0, s20, s10
	v_add_f32_e32 v66, v188, v66
	s_addc_u32 s1, s21, s11
	s_add_u32 s10, s22, s10
	s_addc_u32 s11, s23, s11
	s_waitcnt lgkmcnt(11)
	v_mfma_f32_32x32x16_bf16 v[98:113], v[206:209], v[118:121], v[98:113]
	v_exp_f32_e32 v224, v77
	s_and_b32 s13, s37, 0xff
	v_add_f32_e32 v66, v189, v66
	s_mulk_i32 s13, 0xab
	v_exp_f32_e32 v225, v78
	s_lshr_b32 s13, s13, 9
	v_add_f32_e32 v66, v205, v66
	s_mul_i32 s13, s13, 3
	s_sub_i32 s13, s37, s13
	s_and_b32 s13, s13, 0xff
	s_waitcnt lgkmcnt(10)
	v_mfma_f32_32x32x16_bf16 v[82:97], v[210:213], v[118:121], v[82:97]
	v_exp_f32_e32 v226, v79
	s_lshl_b32 s13, s13, 14
	s_mov_b32 s100, s13
	v_add_f32_e32 v66, v222, v66
	s_add_i32 s42, s36, 0xffffc000
	v_exp_f32_e32 v227, v80
	s_and_b32 s42, s42, 0xc000
	v_add_f32_e32 v66, v223, v66
	s_add_i32 s13, s13, s27
	v_exp_f32_e32 v81, v81
	s_add_i32 s42, s42, s31
	s_mov_b32 m0, s13
	s_waitcnt lgkmcnt(9)
	v_mfma_f32_32x32x16_bf16 v[98:113], v[214:217], v[114:117], v[98:113]
	v_add_f32_e32 v66, v224, v66
	v_add_f32_e32 v66, v225, v66
	global_load_lds_dwordx4 v146, s[0:1]
	v_add_f32_e32 v66, v226, v66
	v_add_f32_e32 v66, v227, v66
	s_mov_b32 m0, s42
	s_nop 0
	global_load_lds_dwordx4 v142, s[10:11]
	s_waitcnt lgkmcnt(8)
	v_mfma_f32_32x32x16_bf16 v[82:97], v[218:221], v[114:117], v[82:97]
	v_add_f32_e32 v130, v81, v66
	s_add_i32 m0, s13, 0x2000
	v_mov_b32_e32 v131, v130
	v_cvt_pk_bf16_f32 v66, v175, v177
	global_load_lds_dwordx4 v144, s[0:1]
	v_cvt_pk_bf16_f32 v67, v192, v195
	v_cvt_pk_bf16_f32 v68, v196, v199
	s_add_i32 m0, s42, 0x2000
	s_nop 0
	global_load_lds_dwordx4 v154, s[10:11]
	v_permlane32_swap_b32_e32 v130, v131
	v_cvt_pk_bf16_f32 v69, v200, v203
	v_permlane32_swap_b32_e32 v66, v68
	v_cvt_pk_bf16_f32 v70, v176, v193
	v_cvt_pk_bf16_f32 v71, v194, v197
	v_cvt_pk_bf16_f32 v72, v198, v201
	v_cvt_pk_bf16_f32 v73, v202, v204
	v_cvt_pk_bf16_f32 v74, v148, v149
	v_cvt_pk_bf16_f32 v75, v150, v151
	v_cvt_pk_bf16_f32 v76, v186, v187
	v_cvt_pk_bf16_f32 v77, v188, v189
	v_cvt_pk_bf16_f32 v78, v205, v222
	v_cvt_pk_bf16_f32 v79, v223, v224
	v_cvt_pk_bf16_f32 v80, v225, v226
	v_cvt_pk_bf16_f32 v81, v227, v81
	v_permlane32_swap_b32_e32 v67, v69
	v_permlane32_swap_b32_e32 v70, v72
	v_permlane32_swap_b32_e32 v71, v73
	v_permlane32_swap_b32_e32 v74, v76
	v_permlane32_swap_b32_e32 v75, v77
	v_permlane32_swap_b32_e32 v78, v80
	v_permlane32_swap_b32_e32 v79, v81
	ds_read_b64_tr_b16 v[204:205], v244 offset:0x200
	ds_read_b64_tr_b16 v[206:207], v244 offset:0xa00
	ds_read_b64_tr_b16 v[208:209], v244 offset:0x1200
	ds_read_b64_tr_b16 v[210:211], v244 offset:0x1a00
	ds_read_b64_tr_b16 v[212:213], v244 offset:0x2200
	ds_read_b64_tr_b16 v[214:215], v244 offset:0x2a00
	ds_read_b64_tr_b16 v[216:217], v244 offset:0x3200
	ds_read_b64_tr_b16 v[218:219], v244 offset:0x3a00
	s_waitcnt lgkmcnt(14)
	v_mfma_f32_32x32x16_bf16 v[18:33], v[66:69], v[228:231], v[18:33]
	v_max_f32_e32 v245, v99, v99
	v_max_f32_e32 v246, v98, v98
	v_max_f32_e32 v245, v246, v245
	v_max3_f32 v245, v245, v100, v101
	v_max3_f32 v245, v245, v102, v103
	v_max3_f32 v245, v245, v104, v105
	v_max3_f32 v245, v245, v106, v107
	v_max3_f32 v245, v245, v108, v109
	s_waitcnt lgkmcnt(12)
; #define SBAR() __builtin_amdgcn_sched_barrier(0)
; __device__ __forceinline__ void partialSM(f32x16& p0, f32x16& p1, float& m_reg, float& mn, float& alpha) {
;   constexpr float C = SCALE * 1.4426950408889634f;
;   float pmax = p0[0]; for (int r = 1; r < 16; ++r) pmax = fmaxf(pmax, p0[r]); for (int r = 0; r < 16; ++r) pmax = fmaxf(pmax, p1[r]);
;   { auto rr = __builtin_amdgcn_permlane32_swap(__float_as_uint(pmax), __float_as_uint(pmax), false, false);
;     pmax = fmaxf(__uint_as_float(rr[0]), __uint_as_float(rr[1])); }
;   if (__builtin_expect(__all(pmax - m_reg <= THR / SCALE), 1)) { mn = m_reg; alpha = 1.f; }
;   else { mn = fmaxf(m_reg, pmax); alpha = __builtin_amdgcn_exp2f((m_reg - mn) * C); m_reg = mn; }
;   float mnC = -mn * C;
;   for (int r = 0; r < 16; ++r) p0[r] = fmaf(p0[r], C, mnC); for (int r = 0; r < 16; ++r) p1[r] = fmaf(p1[r], C, mnC);
;   for (int r = 0; r < 16; ++r) p0[r] = __builtin_amdgcn_exp2f(p0[r]);
; }
; __device__ __forceinline__ void pv_mma(f32x16& od, const VFrag& f, bf16x8 pa0, bf16x8 pa1, bf16x8 pa2, bf16x8 pa3) {
;     ...
;   od = __builtin_amdgcn_mfma_f32_32x32x16_bf16(pa0, PK(f.l0, f.h0), od, 0, 0, 0);
;   od = __builtin_amdgcn_mfma_f32_32x32x16_bf16(pa1, PK(f.l1, f.h1), od, 0, 0, 0);
;   od = __builtin_amdgcn_mfma_f32_32x32x16_bf16(pa2, PK(f.l2, f.h2), od, 0, 0, 0);
;   od = __builtin_amdgcn_mfma_f32_32x32x16_bf16(pa3, PK(f.l3, f.h3), od, 0, 0, 0);
;     ...
; }
; __device__ __forceinline__ void pv_d0(f32x16* o, int vb, bf16x8 pa0, bf16x8 pa1, bf16x8 pa2, bf16x8 pa3) {
;   VFrag fa, fb;
;   v_frag_read<0>(fa, vb);
;   asm volatile("s_waitcnt lgkmcnt(0)" ::: "memory"); SBAR();
;   v_frag_read<1>(fb, vb); SBAR();
;   pv_mma(o[0], fa, pa0, pa1, pa2, pa3); SBAR();
;   asm volatile("s_waitcnt lgkmcnt(0)" ::: "memory"); SBAR();
;   v_frag_read<2>(fa, vb); SBAR();
;   pv_mma(o[1], fb, pa0, pa1, pa2, pa3); SBAR();
;   asm volatile("s_waitcnt lgkmcnt(0)" ::: "memory"); SBAR();
;   v_frag_read<3>(fb, vb); SBAR();
;   pv_mma(o[2], fa, pa0, pa1, pa2, pa3); SBAR();
;   asm volatile("s_waitcnt lgkmcnt(0)" ::: "memory"); SBAR();
;   pv_mma(o[3], fb, pa0, pa1, pa2, pa3);
; }
	v_mfma_f32_32x32x16_bf16 v[18:33], v[70:73], v[232:235], v[18:33]
	v_max3_f32 v245, v245, v110, v111
	v_max3_f32 v245, v245, v112, v113
	v_max3_f32 v245, v245, v82, v83
	v_max3_f32 v245, v245, v84, v85
	v_max3_f32 v245, v245, v86, v87
	v_max3_f32 v245, v245, v88, v89
	v_max3_f32 v245, v245, v90, v91
	v_max3_f32 v245, v245, v92, v93
	s_waitcnt lgkmcnt(10)
	v_mfma_f32_32x32x16_bf16 v[18:33], v[74:77], v[236:239], v[18:33]
	v_max3_f32 v245, v245, v94, v95
	v_max3_f32 v245, v245, v96, v97
	v_mov_b32_e32 v246, v245
	s_nop 1
	v_permlane32_swap_b32_e32 v245, v246
	v_max_f32_e32 v246, v246, v246
	v_max_f32_e32 v245, v245, v245
	v_max_f32_e32 v245, v245, v246
	v_sub_f32_e32 v246, v245, v174
	s_waitcnt lgkmcnt(8)
	v_mfma_f32_32x32x16_bf16 v[18:33], v[78:81], v[240:243], v[18:33]
	v_cmp_ge_f32_e32 vcc, s63, v246
	v_max_f32_e32 v246, v174, v174
	v_max_f32_e32 v245, v246, v245
	v_sub_f32_e32 v246, v174, v245
	v_mul_f32_e32 v246, 0x3e38aa3b, v246
	v_exp_f32_e32 v246, v246
	s_cmp_eq_u64 vcc, exec
	s_cselect_b64 s[0:1], -1, 0
	v_cndmask_b32_e64 v132, v246, 1.0, s[0:1]
	ds_read_b64_tr_b16 v[228:229], v244 offset:0x400
	ds_read_b64_tr_b16 v[230:231], v244 offset:0xc00
	ds_read_b64_tr_b16 v[232:233], v244 offset:0x1400
	ds_read_b64_tr_b16 v[234:235], v244 offset:0x1c00
	ds_read_b64_tr_b16 v[236:237], v244 offset:0x2400
	ds_read_b64_tr_b16 v[238:239], v244 offset:0x2c00
	ds_read_b64_tr_b16 v[240:241], v244 offset:0x3400
	ds_read_b64_tr_b16 v[242:243], v244 offset:0x3c00
	v_cndmask_b32_e64 v133, v245, v174, s[0:1]
	v_mul_f32_e32 v148, 0xbe38aa3b, v133
	s_mov_b32 s44, 0x3e38aa3b
	s_waitcnt lgkmcnt(14)
	v_mfma_f32_32x32x16_bf16 v[50:65], v[66:69], v[204:207], v[50:65]
	v_pk_fma_f32 v[98:99], v[98:99], s[44:45], v[148:149] op_sel_hi:[1,0,0]
	v_pk_fma_f32 v[100:101], v[100:101], s[44:45], v[148:149] op_sel_hi:[1,0,0]
	s_waitcnt lgkmcnt(12)
	v_mfma_f32_32x32x16_bf16 v[50:65], v[70:73], v[208:211], v[50:65]
	v_pk_fma_f32 v[102:103], v[102:103], s[44:45], v[148:149] op_sel_hi:[1,0,0]
	v_pk_fma_f32 v[104:105], v[104:105], s[44:45], v[148:149] op_sel_hi:[1,0,0]
	s_waitcnt lgkmcnt(10)
	v_mfma_f32_32x32x16_bf16 v[50:65], v[74:77], v[212:215], v[50:65]
	v_pk_fma_f32 v[106:107], v[106:107], s[44:45], v[148:149] op_sel_hi:[1,0,0]
	v_pk_fma_f32 v[108:109], v[108:109], s[44:45], v[148:149] op_sel_hi:[1,0,0]
	s_waitcnt lgkmcnt(8)
	v_mfma_f32_32x32x16_bf16 v[50:65], v[78:81], v[216:219], v[50:65]
	v_pk_fma_f32 v[110:111], v[110:111], s[44:45], v[148:149] op_sel_hi:[1,0,0]
	v_pk_fma_f32 v[112:113], v[112:113], s[44:45], v[148:149] op_sel_hi:[1,0,0]
	ds_read_b64_tr_b16 v[204:205], v244 offset:0x600
	ds_read_b64_tr_b16 v[206:207], v244 offset:0xe00
	ds_read_b64_tr_b16 v[208:209], v244 offset:0x1600
	ds_read_b64_tr_b16 v[210:211], v244 offset:0x1e00
	ds_read_b64_tr_b16 v[212:213], v244 offset:0x2600
	ds_read_b64_tr_b16 v[214:215], v244 offset:0x2e00
	ds_read_b64_tr_b16 v[216:217], v244 offset:0x3600
	ds_read_b64_tr_b16 v[218:219], v244 offset:0x3e00
	s_waitcnt lgkmcnt(14)
	v_mfma_f32_32x32x16_bf16 v[34:49], v[66:69], v[228:231], v[34:49]
	v_pk_fma_f32 v[82:83], v[82:83], s[44:45], v[148:149] op_sel_hi:[1,0,0]
	v_pk_fma_f32 v[84:85], v[84:85], s[44:45], v[148:149] op_sel_hi:[1,0,0]
	s_waitcnt lgkmcnt(12)
	v_mfma_f32_32x32x16_bf16 v[34:49], v[70:73], v[232:235], v[34:49]
	v_pk_fma_f32 v[86:87], v[86:87], s[44:45], v[148:149] op_sel_hi:[1,0,0]
	s_add_i32 s13, s36, 0xffff4000
	v_fmamk_f32 v149, v88, 0x3e38aa3b, v148
	s_waitcnt lgkmcnt(10)
	v_mfma_f32_32x32x16_bf16 v[34:49], v[74:77], v[236:239], v[34:49]
	v_fmamk_f32 v150, v89, 0x3e38aa3b, v148
	v_fmamk_f32 v151, v90, 0x3e38aa3b, v148
	v_fmamk_f32 v186, v91, 0x3e38aa3b, v148
	v_fmamk_f32 v187, v92, 0x3e38aa3b, v148
	s_waitcnt lgkmcnt(8)
	v_mfma_f32_32x32x16_bf16 v[34:49], v[78:81], v[240:243], v[34:49]
	v_fmamk_f32 v188, v93, 0x3e38aa3b, v148
	v_fmamk_f32 v189, v94, 0x3e38aa3b, v148
	v_exp_f32_e32 v192, v98
	v_exp_f32_e32 v193, v99
	v_exp_f32_e32 v194, v100
	v_exp_f32_e32 v195, v101
	s_waitcnt lgkmcnt(6)
	v_mfma_f32_32x32x16_bf16 v[2:17], v[66:69], v[204:207], v[2:17]
	v_exp_f32_e32 v196, v102
	v_exp_f32_e32 v197, v103
	v_exp_f32_e32 v198, v104
	v_exp_f32_e32 v199, v105
	s_waitcnt lgkmcnt(4)
	v_mfma_f32_32x32x16_bf16 v[2:17], v[70:73], v[208:211], v[2:17]
	v_exp_f32_e32 v200, v106
	v_exp_f32_e32 v201, v107
	v_exp_f32_e32 v202, v108
	v_exp_f32_e32 v203, v109
	v_exp_f32_e32 v204, v110
	v_exp_f32_e32 v205, v111
	s_waitcnt lgkmcnt(2)
	v_mfma_f32_32x32x16_bf16 v[2:17], v[74:77], v[212:215], v[2:17]
	v_exp_f32_e32 v206, v112
	v_exp_f32_e32 v207, v113
	v_fmamk_f32 v208, v95, 0x3e38aa3b, v148
	v_fmamk_f32 v209, v96, 0x3e38aa3b, v148
	v_fmac_f32_e32 v148, 0x3e38aa3b, v97
	s_waitcnt lgkmcnt(0)
	v_mfma_f32_32x32x16_bf16 v[2:17], v[78:81], v[216:219], v[2:17]
	v_add_u32_e32 v245, s101, v169
	v_add_u32_e32 v246, s101, v170
	v_add_u32_e32 v247, s101, v171
	v_add_u32_e32 v255, s101, v172
	v_cmp_gt_f32_e32 vcc, 1.0, v132
	s_cbranch_vccz .LBB0_774
	s_and_saveexec_b64 s[10:11], s[40:41]
	ds_write_b32 v162, v132 offset:128
	s_or_b64 exec, exec, s[10:11]
	s_waitcnt lgkmcnt(0)
	v_add_u32_e32 v67, s18, v140
	ds_read_b128 v[68:71], v67 offset:224
	ds_read_b128 v[72:75], v67 offset:192
	ds_read_b128 v[76:79], v67 offset:160
	ds_read_b128 v[134:137], v67 offset:128
	s_waitcnt lgkmcnt(0)
	v_pk_mul_f32 v[30:31], v[30:31], v[68:69]
	v_pk_mul_f32 v[26:27], v[26:27], v[72:73]
	v_pk_mul_f32 v[22:23], v[22:23], v[76:77]
	v_pk_mul_f32 v[32:33], v[32:33], v[70:71]
	v_pk_mul_f32 v[28:29], v[28:29], v[74:75]
	v_pk_mul_f32 v[24:25], v[24:25], v[78:79]
	v_pk_mul_f32 v[20:21], v[20:21], v[136:137]
	v_pk_mul_f32 v[18:19], v[18:19], v[134:135]
	v_pk_mul_f32 v[62:63], v[62:63], v[68:69]
	v_pk_mul_f32 v[58:59], v[58:59], v[72:73]
	v_pk_mul_f32 v[54:55], v[54:55], v[76:77]
	v_pk_mul_f32 v[64:65], v[64:65], v[70:71]
	v_pk_mul_f32 v[60:61], v[60:61], v[74:75]
	v_pk_mul_f32 v[56:57], v[56:57], v[78:79]
	v_pk_mul_f32 v[52:53], v[52:53], v[136:137]
	v_pk_mul_f32 v[50:51], v[50:51], v[134:135]
	v_pk_mul_f32 v[46:47], v[46:47], v[68:69]
	v_pk_mul_f32 v[42:43], v[42:43], v[72:73]
	v_pk_mul_f32 v[38:39], v[38:39], v[76:77]
	v_pk_mul_f32 v[48:49], v[48:49], v[70:71]
	v_pk_mul_f32 v[44:45], v[44:45], v[74:75]
	v_pk_mul_f32 v[40:41], v[40:41], v[78:79]
	v_pk_mul_f32 v[36:37], v[36:37], v[136:137]
	v_pk_mul_f32 v[34:35], v[34:35], v[134:135]
	v_pk_mul_f32 v[14:15], v[14:15], v[68:69]
	v_pk_mul_f32 v[10:11], v[10:11], v[72:73]
	v_pk_mul_f32 v[6:7], v[6:7], v[76:77]
	v_pk_mul_f32 v[16:17], v[16:17], v[70:71]
	v_pk_mul_f32 v[12:13], v[12:13], v[74:75]
	v_pk_mul_f32 v[8:9], v[8:9], v[78:79]
	v_pk_mul_f32 v[4:5], v[4:5], v[136:137]
	v_pk_mul_f32 v[2:3], v[2:3], v[134:135]

; #define SBAR() __builtin_amdgcn_sched_barrier(0)
; __device__ __forceinline__ void partialSM(f32x16& p0, f32x16& p1, float& m_reg, float& mn, float& alpha) {
;   constexpr float C = SCALE * 1.4426950408889634f;
;   float pmax = p0[0]; for (int r = 1; r < 16; ++r) pmax = fmaxf(pmax, p0[r]); for (int r = 0; r < 16; ++r) pmax = fmaxf(pmax, p1[r]);
;   { auto rr = __builtin_amdgcn_permlane32_swap(__float_as_uint(pmax), __float_as_uint(pmax), false, false);
;     pmax = fmaxf(__uint_as_float(rr[0]), __uint_as_float(rr[1])); }
;   if (__builtin_expect(__all(pmax - m_reg <= THR / SCALE), 1)) { mn = m_reg; alpha = 1.f; }
;   else { mn = fmaxf(m_reg, pmax); alpha = __builtin_amdgcn_exp2f((m_reg - mn) * C); m_reg = mn; }
;   float mnC = -mn * C;
;   for (int r = 0; r < 16; ++r) p0[r] = fmaf(p0[r], C, mnC); for (int r = 0; r < 16; ++r) p1[r] = fmaf(p1[r], C, mnC);
;   for (int r = 0; r < 16; ++r) p0[r] = __builtin_amdgcn_exp2f(p0[r]);
; }
; __device__ __forceinline__ void pv_mma(f32x16& od, const VFrag& f, bf16x8 pa0, bf16x8 pa1, bf16x8 pa2, bf16x8 pa3) {
;     ...
;   od = __builtin_amdgcn_mfma_f32_32x32x16_bf16(pa0, PK(f.l0, f.h0), od, 0, 0, 0);
;   od = __builtin_amdgcn_mfma_f32_32x32x16_bf16(pa1, PK(f.l1, f.h1), od, 0, 0, 0);
;   od = __builtin_amdgcn_mfma_f32_32x32x16_bf16(pa2, PK(f.l2, f.h2), od, 0, 0, 0);
;   od = __builtin_amdgcn_mfma_f32_32x32x16_bf16(pa3, PK(f.l3, f.h3), od, 0, 0, 0);
;     ...
; }
; __device__ __forceinline__ void pv_d0(f32x16* o, int vb, bf16x8 pa0, bf16x8 pa1, bf16x8 pa2, bf16x8 pa3) {
;   VFrag fa, fb;
;   v_frag_read<0>(fa, vb);
;   asm volatile("s_waitcnt lgkmcnt(0)" ::: "memory"); SBAR();
;   v_frag_read<1>(fb, vb); SBAR();
;   pv_mma(o[0], fa, pa0, pa1, pa2, pa3); SBAR();
;   asm volatile("s_waitcnt lgkmcnt(0)" ::: "memory"); SBAR();
;   v_frag_read<2>(fa, vb); SBAR();
;   pv_mma(o[1], fb, pa0, pa1, pa2, pa3); SBAR();
;   asm volatile("s_waitcnt lgkmcnt(0)" ::: "memory"); SBAR();
;   v_frag_read<3>(fb, vb); SBAR();
;   pv_mma(o[2], fa, pa0, pa1, pa2, pa3); SBAR();
;   asm volatile("s_waitcnt lgkmcnt(0)" ::: "memory"); SBAR();
;   pv_mma(o[3], fb, pa0, pa1, pa2, pa3);
; }
.LBB0_776:
	v_mov_b32_e32 v100, v99
	s_nop 1
	v_permlane32_swap_b32_e32 v99, v100
	v_cvt_pk_bf16_f32 v102, v192, v193
	v_cvt_pk_bf16_f32 v103, v194, v195
	v_cvt_pk_bf16_f32 v104, v196, v197
	v_cvt_pk_bf16_f32 v105, v198, v199
	s_waitcnt lgkmcnt(8)
	v_mfma_f32_32x32x16_bf16 v[66:81], v[174:177], v[114:117], v[66:81]
	v_cvt_pk_bf16_f32 v106, v200, v201
	v_cvt_pk_bf16_f32 v107, v202, v203
	v_cvt_pk_bf16_f32 v108, v204, v205
	v_cvt_pk_bf16_f32 v109, v206, v207
	v_cvt_pk_bf16_f32 v110, v210, v211
	v_cvt_pk_bf16_f32 v111, v212, v213
	v_cvt_pk_bf16_f32 v112, v214, v215
	v_cvt_pk_bf16_f32 v113, v149, v150
	v_cvt_pk_bf16_f32 v134, v151, v186
	v_cvt_pk_bf16_f32 v135, v187, v188
	v_cvt_pk_bf16_f32 v136, v189, v208
	v_cvt_pk_bf16_f32 v137, v209, v148
	v_permlane32_swap_b32_e32 v102, v104
	v_permlane32_swap_b32_e32 v103, v105
	v_permlane32_swap_b32_e32 v106, v108
	v_permlane32_swap_b32_e32 v107, v109
	v_permlane32_swap_b32_e32 v110, v112
	v_permlane32_swap_b32_e32 v111, v113
	v_permlane32_swap_b32_e32 v134, v136
	v_permlane32_swap_b32_e32 v135, v137
	ds_read_b64_tr_b16 v[204:205], v244 offset:0x200
	ds_read_b64_tr_b16 v[206:207], v244 offset:0xa00
	ds_read_b64_tr_b16 v[208:209], v244 offset:0x1200
	ds_read_b64_tr_b16 v[210:211], v244 offset:0x1a00
	ds_read_b64_tr_b16 v[212:213], v244 offset:0x2200
	ds_read_b64_tr_b16 v[214:215], v244 offset:0x2a00
	ds_read_b64_tr_b16 v[216:217], v244 offset:0x3200
	ds_read_b64_tr_b16 v[218:219], v244 offset:0x3a00
	s_waitcnt lgkmcnt(14)
	v_mfma_f32_32x32x16_bf16 v[18:33], v[102:105], v[228:231], v[18:33]
	v_max_f32_e32 v245, v83, v83
	v_max_f32_e32 v246, v82, v82
	v_max_f32_e32 v245, v246, v245
	v_max3_f32 v245, v245, v84, v85
	v_max3_f32 v245, v245, v86, v87
	v_max3_f32 v245, v245, v88, v89
	v_max3_f32 v245, v245, v90, v91
	v_max3_f32 v245, v245, v92, v93
	s_waitcnt lgkmcnt(12)
	v_mfma_f32_32x32x16_bf16 v[18:33], v[106:109], v[232:235], v[18:33]
	v_max3_f32 v245, v245, v94, v95
	v_max3_f32 v245, v245, v96, v97
	v_max3_f32 v245, v245, v66, v67
	v_max3_f32 v245, v245, v68, v69
	v_max3_f32 v245, v245, v70, v71
	v_max3_f32 v245, v245, v72, v73
	v_max3_f32 v245, v245, v74, v75
	v_max3_f32 v245, v245, v76, v77
	s_waitcnt lgkmcnt(10)
	v_mfma_f32_32x32x16_bf16 v[18:33], v[110:113], v[236:239], v[18:33]
	v_max3_f32 v245, v245, v78, v79
	v_max3_f32 v245, v245, v80, v81
	v_mov_b32_e32 v246, v245
	s_nop 1
	v_permlane32_swap_b32_e32 v245, v246
	v_max_f32_e32 v246, v246, v246
	v_max_f32_e32 v245, v245, v245
	v_max_f32_e32 v245, v245, v246
	v_sub_f32_e32 v246, v245, v133
	s_waitcnt lgkmcnt(8)
	v_mfma_f32_32x32x16_bf16 v[18:33], v[134:137], v[240:243], v[18:33]
	v_cmp_ge_f32_e32 vcc, s63, v246
	v_max_f32_e32 v246, v133, v133
	v_max_f32_e32 v245, v246, v245
	v_sub_f32_e32 v246, v133, v245
	v_mul_f32_e32 v246, 0x3e38aa3b, v246
	v_exp_f32_e32 v246, v246
	s_cmp_eq_u64 vcc, exec
	s_cselect_b64 s[0:1], -1, 0
	v_cndmask_b32_e64 v247, v246, 1.0, s[0:1]
	ds_read_b64_tr_b16 v[228:229], v244 offset:0x400
	ds_read_b64_tr_b16 v[230:231], v244 offset:0xc00
	ds_read_b64_tr_b16 v[232:233], v244 offset:0x1400
	ds_read_b64_tr_b16 v[234:235], v244 offset:0x1c00
	ds_read_b64_tr_b16 v[236:237], v244 offset:0x2400
	ds_read_b64_tr_b16 v[238:239], v244 offset:0x2c00
	ds_read_b64_tr_b16 v[240:241], v244 offset:0x3400
	ds_read_b64_tr_b16 v[242:243], v244 offset:0x3c00
	v_cndmask_b32_e64 v174, v245, v133, s[0:1]
	v_mul_f32_e32 v98, 0xbe38aa3b, v174
	s_mov_b32 s46, 0x3e38aa3b
	s_waitcnt lgkmcnt(14)
	v_mfma_f32_32x32x16_bf16 v[50:65], v[102:105], v[204:207], v[50:65]
	v_pk_fma_f32 v[82:83], v[82:83], s[46:47], v[98:99] op_sel_hi:[1,0,0]
	v_pk_fma_f32 v[84:85], v[84:85], s[46:47], v[98:99] op_sel_hi:[1,0,0]
	s_waitcnt lgkmcnt(12)
	v_mfma_f32_32x32x16_bf16 v[50:65], v[106:109], v[208:211], v[50:65]
	v_pk_fma_f32 v[86:87], v[86:87], s[46:47], v[98:99] op_sel_hi:[1,0,0]
	v_pk_fma_f32 v[88:89], v[88:89], s[46:47], v[98:99] op_sel_hi:[1,0,0]
	s_waitcnt lgkmcnt(10)
	v_mfma_f32_32x32x16_bf16 v[50:65], v[110:113], v[212:215], v[50:65]
	v_pk_fma_f32 v[90:91], v[90:91], s[46:47], v[98:99] op_sel_hi:[1,0,0]
	v_pk_fma_f32 v[92:93], v[92:93], s[46:47], v[98:99] op_sel_hi:[1,0,0]
	s_waitcnt lgkmcnt(8)
	v_mfma_f32_32x32x16_bf16 v[50:65], v[134:137], v[216:219], v[50:65]
	v_pk_fma_f32 v[94:95], v[94:95], s[46:47], v[98:99] op_sel_hi:[1,0,0]
	v_pk_fma_f32 v[96:97], v[96:97], s[46:47], v[98:99] op_sel_hi:[1,0,0]
	ds_read_b64_tr_b16 v[204:205], v244 offset:0x600
	ds_read_b64_tr_b16 v[206:207], v244 offset:0xe00
	ds_read_b64_tr_b16 v[208:209], v244 offset:0x1600
	ds_read_b64_tr_b16 v[210:211], v244 offset:0x1e00
	ds_read_b64_tr_b16 v[212:213], v244 offset:0x2600
	ds_read_b64_tr_b16 v[214:215], v244 offset:0x2e00
	ds_read_b64_tr_b16 v[216:217], v244 offset:0x3600
	ds_read_b64_tr_b16 v[218:219], v244 offset:0x3e00
	s_waitcnt lgkmcnt(14)
	v_mfma_f32_32x32x16_bf16 v[34:49], v[102:105], v[228:231], v[34:49]
	v_pk_fma_f32 v[80:81], v[80:81], s[46:47], v[98:99] op_sel_hi:[1,0,0]
	v_pk_fma_f32 v[78:79], v[78:79], s[46:47], v[98:99] op_sel_hi:[1,0,0]
	s_waitcnt lgkmcnt(12)
	v_mfma_f32_32x32x16_bf16 v[34:49], v[106:109], v[232:235], v[34:49]
	v_pk_fma_f32 v[76:77], v[76:77], s[46:47], v[98:99] op_sel_hi:[1,0,0]
	v_pk_fma_f32 v[74:75], v[74:75], s[46:47], v[98:99] op_sel_hi:[1,0,0]
	v_pk_fma_f32 v[72:73], v[72:73], s[46:47], v[98:99] op_sel_hi:[1,0,0]
	s_waitcnt lgkmcnt(10)
	v_mfma_f32_32x32x16_bf16 v[34:49], v[110:113], v[236:239], v[34:49]
	v_pk_fma_f32 v[70:71], v[70:71], s[46:47], v[98:99] op_sel_hi:[1,0,0]
	v_pk_fma_f32 v[68:69], v[68:69], s[46:47], v[98:99] op_sel_hi:[1,0,0]
	v_pk_fma_f32 v[66:67], v[66:67], s[46:47], v[98:99] op_sel_hi:[1,0,0]
	s_waitcnt lgkmcnt(8)
	v_mfma_f32_32x32x16_bf16 v[34:49], v[134:137], v[240:243], v[34:49]
	v_exp_f32_e32 v175, v82
	v_exp_f32_e32 v177, v83
	v_exp_f32_e32 v192, v84
	s_waitcnt lgkmcnt(6)
	v_mfma_f32_32x32x16_bf16 v[2:17], v[102:105], v[204:207], v[2:17]
	v_mov_b32_e32 v205, v247
	v_exp_f32_e32 v204, v97
	v_exp_f32_e32 v195, v85
	v_exp_f32_e32 v196, v86
	v_exp_f32_e32 v199, v87
	v_exp_f32_e32 v200, v88
	s_waitcnt lgkmcnt(4)
	v_mfma_f32_32x32x16_bf16 v[2:17], v[106:109], v[208:211], v[2:17]
	v_exp_f32_e32 v203, v89
	v_exp_f32_e32 v176, v90
	v_exp_f32_e32 v193, v91
	v_exp_f32_e32 v194, v92
	s_waitcnt lgkmcnt(2)
	v_mfma_f32_32x32x16_bf16 v[2:17], v[110:113], v[212:215], v[2:17]
	v_exp_f32_e32 v197, v93
	v_exp_f32_e32 v198, v94
	v_exp_f32_e32 v201, v95
	v_exp_f32_e32 v202, v96
	s_waitcnt lgkmcnt(0)
	v_mfma_f32_32x32x16_bf16 v[2:17], v[134:137], v[216:219], v[2:17]
	v_add_u32_e32 v245, s100, v169
	v_add_u32_e32 v246, s100, v170
	v_add_u32_e32 v247, s100, v171
	v_add_u32_e32 v255, s100, v172
	v_cmp_gt_f32_e32 vcc, 1.0, v205
	s_cbranch_vccz .LBB0_780
	s_and_saveexec_b64 s[12:13], s[40:41]
	ds_write_b32 v162, v205 offset:128
	s_or_b64 exec, exec, s[12:13]
	s_waitcnt lgkmcnt(0)
	v_add_u32_e32 v101, s18, v140
	ds_read_b128 v[102:105], v101 offset:224
	ds_read_b128 v[106:109], v101 offset:192
	ds_read_b128 v[110:113], v101 offset:160
	ds_read_b128 v[134:137], v101 offset:128
	s_waitcnt lgkmcnt(0)
	v_pk_mul_f32 v[30:31], v[30:31], v[102:103]
	v_pk_mul_f32 v[26:27], v[26:27], v[106:107]
	v_pk_mul_f32 v[22:23], v[22:23], v[110:111]
	v_pk_mul_f32 v[32:33], v[32:33], v[104:105]
	v_pk_mul_f32 v[28:29], v[28:29], v[108:109]
	v_pk_mul_f32 v[24:25], v[24:25], v[112:113]
	v_pk_mul_f32 v[20:21], v[20:21], v[136:137]
	v_pk_mul_f32 v[18:19], v[18:19], v[134:135]
	v_pk_mul_f32 v[62:63], v[62:63], v[102:103]
	v_pk_mul_f32 v[58:59], v[58:59], v[106:107]
	v_pk_mul_f32 v[54:55], v[54:55], v[110:111]
	v_pk_mul_f32 v[64:65], v[64:65], v[104:105]
	v_pk_mul_f32 v[60:61], v[60:61], v[108:109]
	v_pk_mul_f32 v[56:57], v[56:57], v[112:113]
	v_pk_mul_f32 v[52:53], v[52:53], v[136:137]
	v_pk_mul_f32 v[50:51], v[50:51], v[134:135]
	v_pk_mul_f32 v[46:47], v[46:47], v[102:103]
	v_pk_mul_f32 v[42:43], v[42:43], v[106:107]
	v_pk_mul_f32 v[38:39], v[38:39], v[110:111]
	v_pk_mul_f32 v[48:49], v[48:49], v[104:105]
	v_pk_mul_f32 v[44:45], v[44:45], v[108:109]
	v_pk_mul_f32 v[40:41], v[40:41], v[112:113]
	v_pk_mul_f32 v[36:37], v[36:37], v[136:137]
	v_pk_mul_f32 v[34:35], v[34:35], v[134:135]
	v_pk_mul_f32 v[14:15], v[14:15], v[102:103]
	v_pk_mul_f32 v[10:11], v[10:11], v[106:107]
	v_pk_mul_f32 v[6:7], v[6:7], v[110:111]
	v_pk_mul_f32 v[16:17], v[16:17], v[104:105]
	v_pk_mul_f32 v[12:13], v[12:13], v[108:109]
	v_pk_mul_f32 v[8:9], v[8:9], v[112:113]
	v_pk_mul_f32 v[4:5], v[4:5], v[136:137]
	v_pk_mul_f32 v[2:3], v[2:3], v[134:135]
